# adds: G1 copy-out segment descriptor decoded once per tile and stepped by one head slot for segments 1-3 (full decode kept for the K/V^T boundary tile)
# baseline (speedup 1.0000x reference)
; template <int CT>
; DI SegDesc seg_decode(const Params& p, int f0) {
;     SegDesc s; s.dsh = 0; s.ld = 64; s.kind = 0; s.base = nullptr;
;   if (f0 < 4608) {
;     int which = f0 / 1536, f = f0 % 1536, g = f >> 9, h = (f & 511) >> 6, slot = g * 8 + h;
;     s.dsh = g * 2;
;     if (which == 0) { s.kind = 1; s.base = WSU(QA) + (size_t)slot * CT * 64; }
;     else if (which == 1) { s.kind = 1; s.base = WSU(KA) + (size_t)slot * CT * 64; }
;     else { s.kind = 2; s.base = WSU(VTA) + (size_t)slot * 64 * CT; }
;   } else if (f0 < 5120) { s.base = WSU(AG) + (f0 - 4608); s.ld = 512; }
;   else if (f0 < 5632) { s.kind = 1; s.base = WSU(QB) + (size_t)((f0 - 5120) >> 6) * CT * 64; }
;   else if (f0 < 5760) { s.kind = 1; s.base = WSU(KB) + (size_t)((f0 - 5632) >> 6) * CT * 64; }
;   else if (f0 < 5888) { s.kind = 2; s.base = WSU(VTB) + (size_t)((f0 - 5760) >> 6) * 64 * CT; }
;   else if (f0 < 6400) { s.base = WSU(BG) + (f0 - 5888); s.ld = 512; }
;   else if (f0 < 7424) { s.base = WSU(MGA) + (f0 - 6400); s.ld = 1024; }
;   else { s.base = WSU(MGB) + (f0 - 7424); s.ld = 1024; }
;   return s;
; template <int CT>
; DI void phase_g1(int c, int l) {
;     ...
;     for (int seg = 0; seg < 4; ++seg) {
;       const SegDesc sd = seg_decode<CT>(p, fbase + seg * 64);
;       if (sd.kind == 2) {
.LBB0_524:
	s_cmp_eq_u32 s73, 0
	s_cbranch_scc1 .Lseg_full
	s_cmp_eq_u32 s84, 22
	s_cbranch_scc1 .Lseg_full
	s_add_u32 s6, s6, 0x400000
	s_addc_u32 s7, s7, 0
	s_mov_b64 s[26:27], -1
	s_cmp_gt_i32 s74, 1
	s_cbranch_scc1 .LBB0_549
	s_branch .LBB0_563

; #define LOAD_PARAMS() KParams kq_ = (KParams)__builtin_amdgcn_kernarg_segment_ptr(); asm volatile("" : "+s"(kq_)); const Params p = *kq_
; template <int CT>
; __global__ void __launch_bounds__(NTHREADS) mega_kernel(Params p) {
;     ...
; #pragma unroll 1
;   for (int ph = 0; ph < nph; ++ph) {
;     run_phase<CT>(ph);
;     if (ph + 1 < nph) {
;       LOAD_PARAMS();
;       xcd_barrier((unsigned*)(p.ws + WS<CT>::bar), x, nloc, nx, k);
;       ++k;
;     }
;   }
; }
.LBB0_726:
	s_endpgm
	s_nop 0
	s_nop 0
	s_nop 0
	s_nop 0
	s_nop 0
	s_nop 0
	s_nop 0
	s_nop 0
	s_nop 0
	s_nop 0
	s_nop 0
	s_nop 0
	s_nop 0
	s_nop 0
	s_nop 0
	s_nop 0
	s_nop 0
	s_nop 0
	s_nop 0
	s_nop 0
	s_nop 0
	s_nop 0
	s_nop 0
	s_nop 0
	s_nop 0
	s_nop 0
	s_nop 0
	s_nop 0
	s_nop 0
	s_nop 0
	s_nop 0
	s_nop 0
	s_nop 0
	s_nop 0
	s_nop 0
	s_nop 0
	s_nop 0
	s_nop 0
	s_nop 0
	s_endpgm
